# grid barrier: non-leader workgroups poll the cross-XCD release generation directly instead of waiting for their XCD leader to republish it (one atomic + one poll hop less per barrier)
# speedup vs baseline: 1.0117x; 1.0117x over previous
; __device__ __forceinline__ unsigned xb_ld(unsigned* p)              { return __hip_atomic_load(p, __ATOMIC_RELAXED, __HIP_MEMORY_SCOPE_AGENT); }
; __device__ __forceinline__ unsigned xb_add(unsigned* p, unsigned v) { return __hip_atomic_fetch_add(p, v, __ATOMIC_RELAXED, __HIP_MEMORY_SCOPE_AGENT); }
; #define XB_SPIN(cond, bar) do { unsigned _sp = 0; while (cond) { __builtin_amdgcn_s_sleep(1); \
;     if ((++_sp & 255u) == 0u) { if (xb_ld(&(bar)[XB_TMO])) break; if (_sp > XB_SPIN_CAP) { atomicAdd(&(bar)[XB_TMO], 1u); break; } } } } while (0)
; __device__ __forceinline__ void xcd_barrier(const XcdBarrier& b) {
;     ...
;         const unsigned old = xb_add(&bar[XB_XSUB(b.x)], 1u);
;         const unsigned gen = old / nloc;
;         if (old + 1u == (gen + 1u) * nloc) {
;             __builtin_amdgcn_fence(__ATOMIC_RELEASE, "agent");
;             asm volatile("s_waitcnt vmcnt(0)" ::: "memory");
;             const unsigned og = xb_add(&bar[XB_TOP], 1u);
;             const unsigned tg = og / nx;
;             if (og + 1u == (tg + 1u) * nx) xb_add(&bar[XB_TOPGEN], 1u);
;             else XB_SPIN(xb_ld(&bar[XB_TOPGEN]) == tg, bar);
;             __builtin_amdgcn_fence(__ATOMIC_ACQUIRE, "agent");
;             xb_add(&bar[XB_XGEN(b.x)], 1u);
;             asm volatile("s_waitcnt vmcnt(0)" ::: "memory");
;         } else {
;             XB_SPIN(xb_ld(&bar[XB_XGEN(b.x)]) == gen, bar);
.LBB0_264:
	s_or_b64 exec, exec, s[16:17]
	v_cvt_f32_u32_e32 v4, v2
	s_waitcnt vmcnt(0)
	v_readfirstlane_b32 s14, v3
	v_sub_u32_e32 v3, 0, v2
	v_rcp_iflag_f32_e32 v4, v4
	v_add_u32_e32 v5, s14, v1
	v_mul_f32_e32 v4, 0x4f7ffffe, v4
	v_cvt_u32_f32_e32 v4, v4
	v_mul_lo_u32 v1, v3, v4
	v_mul_hi_u32 v1, v4, v1
	v_add_u32_e32 v1, v4, v1
	v_mul_hi_u32 v1, v5, v1
	v_mul_lo_u32 v3, v1, v2
	v_sub_u32_e32 v3, v5, v3
	v_add_u32_e32 v4, 1, v1
	v_cmp_ge_u32_e32 vcc, v3, v2
	s_nop 1
	v_cndmask_b32_e32 v1, v1, v4, vcc
	v_sub_u32_e32 v4, v3, v2
	v_cndmask_b32_e32 v3, v3, v4, vcc
	v_add_u32_e32 v4, 1, v1
	v_cmp_ge_u32_e32 vcc, v3, v2
	v_add_u32_e32 v3, 1, v5
	s_nop 0
	v_cndmask_b32_e32 v1, v1, v4, vcc
	v_mul_lo_u32 v4, v2, v1
	v_add_u32_e32 v2, v4, v2
	v_cmp_ne_u32_e32 vcc, v3, v2
	s_and_saveexec_b64 s[14:15], vcc
	s_xor_b64 s[16:17], exec, s[14:15]
	s_cbranch_execz .LBB0_278
	s_waitcnt lgkmcnt(0)
	v_mov_b32_e32 v0, 0x3100
	global_load_dword v0, v0, s[10:11] offset:1024 sc1
	s_add_u32 s26, s10, 0x3500
	s_addc_u32 s27, s11, 0
	s_waitcnt vmcnt(0)
	v_cmp_eq_u32_e32 vcc, v0, v1
	s_and_saveexec_b64 s[24:25], vcc
	s_cbranch_execz .LBB0_277
	s_mov_b32 s19, 1
	s_mov_b64 s[30:31], 0
	s_branch .LBB0_268

; __device__ __forceinline__ unsigned xb_ld(unsigned* p)              { return __hip_atomic_load(p, __ATOMIC_RELAXED, __HIP_MEMORY_SCOPE_AGENT); }
; __device__ __forceinline__ unsigned xb_add(unsigned* p, unsigned v) { return __hip_atomic_fetch_add(p, v, __ATOMIC_RELAXED, __HIP_MEMORY_SCOPE_AGENT); }
; #define XB_SPIN(cond, bar) do { unsigned _sp = 0; while (cond) { __builtin_amdgcn_s_sleep(1); \
;     if ((++_sp & 255u) == 0u) { if (xb_ld(&(bar)[XB_TMO])) break; if (_sp > XB_SPIN_CAP) { atomicAdd(&(bar)[XB_TMO], 1u); break; } } } } while (0)
; __device__ __forceinline__ void xcd_barrier(const XcdBarrier& b) {
;     ...
;         const unsigned old = xb_add(&bar[XB_XSUB(b.x)], 1u);
;         const unsigned gen = old / nloc;
;         if (old + 1u == (gen + 1u) * nloc) {
;             __builtin_amdgcn_fence(__ATOMIC_RELEASE, "agent");
;             asm volatile("s_waitcnt vmcnt(0)" ::: "memory");
;             const unsigned og = xb_add(&bar[XB_TOP], 1u);
;             const unsigned tg = og / nx;
;             if (og + 1u == (tg + 1u) * nx) xb_add(&bar[XB_TOPGEN], 1u);
;             else XB_SPIN(xb_ld(&bar[XB_TOPGEN]) == tg, bar);
;             __builtin_amdgcn_fence(__ATOMIC_ACQUIRE, "agent");
;             xb_add(&bar[XB_XGEN(b.x)], 1u);
;             asm volatile("s_waitcnt vmcnt(0)" ::: "memory");
;         } else {
;             XB_SPIN(xb_ld(&bar[XB_XGEN(b.x)]) == gen, bar);
.LBB0_484:
	s_or_b64 exec, exec, s[14:15]
	v_cvt_f32_u32_e32 v4, v2
	s_waitcnt vmcnt(0)
	v_readfirstlane_b32 s12, v3
	v_sub_u32_e32 v3, 0, v2
	v_rcp_iflag_f32_e32 v4, v4
	v_add_u32_e32 v5, s12, v1
	v_mul_f32_e32 v4, 0x4f7ffffe, v4
	v_cvt_u32_f32_e32 v4, v4
	v_mul_lo_u32 v1, v3, v4
	v_mul_hi_u32 v1, v4, v1
	v_add_u32_e32 v1, v4, v1
	v_mul_hi_u32 v1, v5, v1
	v_mul_lo_u32 v3, v1, v2
	v_sub_u32_e32 v3, v5, v3
	v_add_u32_e32 v4, 1, v1
	v_cmp_ge_u32_e32 vcc, v3, v2
	s_nop 1
	v_cndmask_b32_e32 v1, v1, v4, vcc
	v_sub_u32_e32 v4, v3, v2
	v_cndmask_b32_e32 v3, v3, v4, vcc
	v_add_u32_e32 v4, 1, v1
	v_cmp_ge_u32_e32 vcc, v3, v2
	v_add_u32_e32 v3, 1, v5
	s_nop 0
	v_cndmask_b32_e32 v1, v1, v4, vcc
	v_mul_lo_u32 v4, v2, v1
	v_add_u32_e32 v2, v4, v2
	v_cmp_ne_u32_e32 vcc, v3, v2
	s_and_saveexec_b64 s[12:13], vcc
	s_xor_b64 s[12:13], exec, s[12:13]
	s_cbranch_execz .LBB0_498
	s_waitcnt lgkmcnt(0)
	v_mov_b32_e32 v0, 0x3100
	global_load_dword v0, v0, s[8:9] offset:1024 sc1
	s_add_u32 s24, s8, 0x3500
	s_addc_u32 s25, s9, 0
	s_waitcnt vmcnt(0)
	v_cmp_eq_u32_e32 vcc, v0, v1
	s_and_saveexec_b64 s[16:17], vcc
	s_cbranch_execz .LBB0_497
	s_mov_b32 s18, 1
	s_mov_b64 s[26:27], 0
	s_branch .LBB0_488

; __device__ __forceinline__ unsigned xb_ld(unsigned* p)              { return __hip_atomic_load(p, __ATOMIC_RELAXED, __HIP_MEMORY_SCOPE_AGENT); }
; __device__ __forceinline__ unsigned xb_add(unsigned* p, unsigned v) { return __hip_atomic_fetch_add(p, v, __ATOMIC_RELAXED, __HIP_MEMORY_SCOPE_AGENT); }
; #define XB_SPIN(cond, bar) do { unsigned _sp = 0; while (cond) { __builtin_amdgcn_s_sleep(1); \
;     if ((++_sp & 255u) == 0u) { if (xb_ld(&(bar)[XB_TMO])) break; if (_sp > XB_SPIN_CAP) { atomicAdd(&(bar)[XB_TMO], 1u); break; } } } } while (0)
; __device__ __forceinline__ void xcd_barrier(const XcdBarrier& b) {
;     ...
;         const unsigned old = xb_add(&bar[XB_XSUB(b.x)], 1u);
;         const unsigned gen = old / nloc;
;         if (old + 1u == (gen + 1u) * nloc) {
;             __builtin_amdgcn_fence(__ATOMIC_RELEASE, "agent");
;             asm volatile("s_waitcnt vmcnt(0)" ::: "memory");
;             const unsigned og = xb_add(&bar[XB_TOP], 1u);
;             const unsigned tg = og / nx;
;             if (og + 1u == (tg + 1u) * nx) xb_add(&bar[XB_TOPGEN], 1u);
;             else XB_SPIN(xb_ld(&bar[XB_TOPGEN]) == tg, bar);
;             __builtin_amdgcn_fence(__ATOMIC_ACQUIRE, "agent");
;             xb_add(&bar[XB_XGEN(b.x)], 1u);
;             asm volatile("s_waitcnt vmcnt(0)" ::: "memory");
;         } else {
;             XB_SPIN(xb_ld(&bar[XB_XGEN(b.x)]) == gen, bar);
.LBB0_599:
	s_or_b64 exec, exec, s[14:15]
	v_cvt_f32_u32_e32 v4, v2
	s_waitcnt vmcnt(0)
	v_readfirstlane_b32 s12, v3
	v_sub_u32_e32 v3, 0, v2
	v_rcp_iflag_f32_e32 v4, v4
	v_add_u32_e32 v5, s12, v1
	v_mul_f32_e32 v4, 0x4f7ffffe, v4
	v_cvt_u32_f32_e32 v4, v4
	v_mul_lo_u32 v1, v3, v4
	v_mul_hi_u32 v1, v4, v1
	v_add_u32_e32 v1, v4, v1
	v_mul_hi_u32 v1, v5, v1
	v_mul_lo_u32 v3, v1, v2
	v_sub_u32_e32 v3, v5, v3
	v_add_u32_e32 v4, 1, v1
	v_cmp_ge_u32_e32 vcc, v3, v2
	s_nop 1
	v_cndmask_b32_e32 v1, v1, v4, vcc
	v_sub_u32_e32 v4, v3, v2
	v_cndmask_b32_e32 v3, v3, v4, vcc
	v_add_u32_e32 v4, 1, v1
	v_cmp_ge_u32_e32 vcc, v3, v2
	v_add_u32_e32 v3, 1, v5
	s_nop 0
	v_cndmask_b32_e32 v1, v1, v4, vcc
	v_mul_lo_u32 v4, v2, v1
	v_add_u32_e32 v2, v4, v2
	v_cmp_ne_u32_e32 vcc, v3, v2
	s_and_saveexec_b64 s[12:13], vcc
	s_xor_b64 s[12:13], exec, s[12:13]
	s_cbranch_execz .LBB0_613
	s_waitcnt lgkmcnt(0)
	v_mov_b32_e32 v0, 0x3100
	global_load_dword v0, v0, s[8:9] offset:1024 sc1
	s_add_u32 s18, s8, 0x3500
	s_addc_u32 s19, s9, 0
	s_waitcnt vmcnt(0)
	v_cmp_eq_u32_e32 vcc, v0, v1
	s_and_saveexec_b64 s[16:17], vcc
	s_cbranch_execz .LBB0_612
	s_mov_b32 s43, 1
	s_mov_b64 s[24:25], 0
	s_branch .LBB0_603

; __device__ __forceinline__ unsigned xb_ld(unsigned* p)              { return __hip_atomic_load(p, __ATOMIC_RELAXED, __HIP_MEMORY_SCOPE_AGENT); }
; __device__ __forceinline__ unsigned xb_add(unsigned* p, unsigned v) { return __hip_atomic_fetch_add(p, v, __ATOMIC_RELAXED, __HIP_MEMORY_SCOPE_AGENT); }
; #define XB_SPIN(cond, bar) do { unsigned _sp = 0; while (cond) { __builtin_amdgcn_s_sleep(1); \
;     if ((++_sp & 255u) == 0u) { if (xb_ld(&(bar)[XB_TMO])) break; if (_sp > XB_SPIN_CAP) { atomicAdd(&(bar)[XB_TMO], 1u); break; } } } } while (0)
; __device__ __forceinline__ void xcd_barrier(const XcdBarrier& b) {
;     ...
;         const unsigned old = xb_add(&bar[XB_XSUB(b.x)], 1u);
;         const unsigned gen = old / nloc;
;         if (old + 1u == (gen + 1u) * nloc) {
;             __builtin_amdgcn_fence(__ATOMIC_RELEASE, "agent");
;             asm volatile("s_waitcnt vmcnt(0)" ::: "memory");
;             const unsigned og = xb_add(&bar[XB_TOP], 1u);
;             const unsigned tg = og / nx;
;             if (og + 1u == (tg + 1u) * nx) xb_add(&bar[XB_TOPGEN], 1u);
;             else XB_SPIN(xb_ld(&bar[XB_TOPGEN]) == tg, bar);
;             __builtin_amdgcn_fence(__ATOMIC_ACQUIRE, "agent");
;             xb_add(&bar[XB_XGEN(b.x)], 1u);
;             asm volatile("s_waitcnt vmcnt(0)" ::: "memory");
;         } else {
;             XB_SPIN(xb_ld(&bar[XB_XGEN(b.x)]) == gen, bar);
.LBB0_1013:
	s_or_b64 exec, exec, s[12:13]
	v_cvt_f32_u32_e32 v4, v2
	s_waitcnt vmcnt(0)
	v_readfirstlane_b32 s10, v3
	v_sub_u32_e32 v3, 0, v2
	v_rcp_iflag_f32_e32 v4, v4
	v_add_u32_e32 v5, s10, v1
	v_mul_f32_e32 v4, 0x4f7ffffe, v4
	v_cvt_u32_f32_e32 v4, v4
	v_mul_lo_u32 v1, v3, v4
	v_mul_hi_u32 v1, v4, v1
	v_add_u32_e32 v1, v4, v1
	v_mul_hi_u32 v1, v5, v1
	v_mul_lo_u32 v3, v1, v2
	v_sub_u32_e32 v3, v5, v3
	v_add_u32_e32 v4, 1, v1
	v_cmp_ge_u32_e32 vcc, v3, v2
	s_nop 1
	v_cndmask_b32_e32 v1, v1, v4, vcc
	v_sub_u32_e32 v4, v3, v2
	v_cndmask_b32_e32 v3, v3, v4, vcc
	v_add_u32_e32 v4, 1, v1
	v_cmp_ge_u32_e32 vcc, v3, v2
	v_add_u32_e32 v3, 1, v5
	s_nop 0
	v_cndmask_b32_e32 v1, v1, v4, vcc
	v_mul_lo_u32 v4, v2, v1
	v_add_u32_e32 v2, v4, v2
	v_cmp_ne_u32_e32 vcc, v3, v2
	s_and_saveexec_b64 s[10:11], vcc
	s_xor_b64 s[10:11], exec, s[10:11]
	s_cbranch_execz .LBB0_1027
	s_waitcnt lgkmcnt(0)
	v_mov_b32_e32 v0, 0x3100
	global_load_dword v0, v0, s[6:7] offset:1024 sc1
	s_add_u32 s16, s6, 0x3500
	s_addc_u32 s17, s7, 0
	s_waitcnt vmcnt(0)
	v_cmp_eq_u32_e32 vcc, v0, v1
	s_and_saveexec_b64 s[12:13], vcc
	s_cbranch_execz .LBB0_1026
	s_mov_b32 s36, 1
	s_mov_b64 s[18:19], 0
	s_branch .LBB0_1017

; __device__ __forceinline__ unsigned xb_ld(unsigned* p)              { return __hip_atomic_load(p, __ATOMIC_RELAXED, __HIP_MEMORY_SCOPE_AGENT); }
; __device__ __forceinline__ unsigned xb_add(unsigned* p, unsigned v) { return __hip_atomic_fetch_add(p, v, __ATOMIC_RELAXED, __HIP_MEMORY_SCOPE_AGENT); }
; #define XB_SPIN(cond, bar) do { unsigned _sp = 0; while (cond) { __builtin_amdgcn_s_sleep(1); \
;     if ((++_sp & 255u) == 0u) { if (xb_ld(&(bar)[XB_TMO])) break; if (_sp > XB_SPIN_CAP) { atomicAdd(&(bar)[XB_TMO], 1u); break; } } } } while (0)
; __device__ __forceinline__ void xcd_barrier(const XcdBarrier& b) {
;     ...
;         const unsigned old = xb_add(&bar[XB_XSUB(b.x)], 1u);
;         const unsigned gen = old / nloc;
;         if (old + 1u == (gen + 1u) * nloc) {
;             __builtin_amdgcn_fence(__ATOMIC_RELEASE, "agent");
;             asm volatile("s_waitcnt vmcnt(0)" ::: "memory");
;             const unsigned og = xb_add(&bar[XB_TOP], 1u);
;             const unsigned tg = og / nx;
;             if (og + 1u == (tg + 1u) * nx) xb_add(&bar[XB_TOPGEN], 1u);
;             else XB_SPIN(xb_ld(&bar[XB_TOPGEN]) == tg, bar);
;             __builtin_amdgcn_fence(__ATOMIC_ACQUIRE, "agent");
;             xb_add(&bar[XB_XGEN(b.x)], 1u);
;             asm volatile("s_waitcnt vmcnt(0)" ::: "memory");
;         } else {
;             XB_SPIN(xb_ld(&bar[XB_XGEN(b.x)]) == gen, bar);
.LBB0_1139:
	s_or_b64 exec, exec, s[16:17]
	v_cvt_f32_u32_e32 v4, v2
	s_waitcnt vmcnt(0)
	v_readfirstlane_b32 s14, v3
	v_sub_u32_e32 v3, 0, v2
	v_rcp_iflag_f32_e32 v4, v4
	v_add_u32_e32 v5, s14, v1
	v_mul_f32_e32 v4, 0x4f7ffffe, v4
	v_cvt_u32_f32_e32 v4, v4
	v_mul_lo_u32 v1, v3, v4
	v_mul_hi_u32 v1, v4, v1
	v_add_u32_e32 v1, v4, v1
	v_mul_hi_u32 v1, v5, v1
	v_mul_lo_u32 v3, v1, v2
	v_sub_u32_e32 v3, v5, v3
	v_add_u32_e32 v4, 1, v1
	v_cmp_ge_u32_e32 vcc, v3, v2
	s_nop 1
	v_cndmask_b32_e32 v1, v1, v4, vcc
	v_sub_u32_e32 v4, v3, v2
	v_cndmask_b32_e32 v3, v3, v4, vcc
	v_add_u32_e32 v4, 1, v1
	v_cmp_ge_u32_e32 vcc, v3, v2
	v_add_u32_e32 v3, 1, v5
	s_nop 0
	v_cndmask_b32_e32 v1, v1, v4, vcc
	v_mul_lo_u32 v4, v2, v1
	v_add_u32_e32 v2, v4, v2
	v_cmp_ne_u32_e32 vcc, v3, v2
	s_and_saveexec_b64 s[14:15], vcc
	s_xor_b64 s[16:17], exec, s[14:15]
	s_cbranch_execz .LBB0_1153
	s_waitcnt lgkmcnt(0)
	v_mov_b32_e32 v0, 0x3100
	global_load_dword v0, v0, s[10:11] offset:1024 sc1
	s_add_u32 s24, s10, 0x3500
	s_addc_u32 s25, s11, 0
	s_waitcnt vmcnt(0)
	v_cmp_eq_u32_e32 vcc, v0, v1
	s_and_saveexec_b64 s[18:19], vcc
	s_cbranch_execz .LBB0_1152
	s_mov_b32 s45, 1
	s_mov_b64 s[26:27], 0
	s_branch .LBB0_1143

; __device__ __forceinline__ unsigned xb_ld(unsigned* p)              { return __hip_atomic_load(p, __ATOMIC_RELAXED, __HIP_MEMORY_SCOPE_AGENT); }
; __device__ __forceinline__ unsigned xb_add(unsigned* p, unsigned v) { return __hip_atomic_fetch_add(p, v, __ATOMIC_RELAXED, __HIP_MEMORY_SCOPE_AGENT); }
; #define XB_SPIN(cond, bar) do { unsigned _sp = 0; while (cond) { __builtin_amdgcn_s_sleep(1); \
;     if ((++_sp & 255u) == 0u) { if (xb_ld(&(bar)[XB_TMO])) break; if (_sp > XB_SPIN_CAP) { atomicAdd(&(bar)[XB_TMO], 1u); break; } } } } while (0)
; __device__ __forceinline__ void xcd_barrier(const XcdBarrier& b) {
;     ...
;         const unsigned old = xb_add(&bar[XB_XSUB(b.x)], 1u);
;         const unsigned gen = old / nloc;
;         if (old + 1u == (gen + 1u) * nloc) {
;             __builtin_amdgcn_fence(__ATOMIC_RELEASE, "agent");
;             asm volatile("s_waitcnt vmcnt(0)" ::: "memory");
;             const unsigned og = xb_add(&bar[XB_TOP], 1u);
;             const unsigned tg = og / nx;
;             if (og + 1u == (tg + 1u) * nx) xb_add(&bar[XB_TOPGEN], 1u);
;             else XB_SPIN(xb_ld(&bar[XB_TOPGEN]) == tg, bar);
;             __builtin_amdgcn_fence(__ATOMIC_ACQUIRE, "agent");
;             xb_add(&bar[XB_XGEN(b.x)], 1u);
;             asm volatile("s_waitcnt vmcnt(0)" ::: "memory");
;         } else {
;             XB_SPIN(xb_ld(&bar[XB_XGEN(b.x)]) == gen, bar);
.LBB0_1428:
	s_or_b64 exec, exec, s[14:15]
	v_cvt_f32_u32_e32 v4, v2
	s_waitcnt vmcnt(0)
	v_readfirstlane_b32 s12, v3
	v_sub_u32_e32 v3, 0, v2
	v_rcp_iflag_f32_e32 v4, v4
	v_add_u32_e32 v5, s12, v1
	v_mul_f32_e32 v4, 0x4f7ffffe, v4
	v_cvt_u32_f32_e32 v4, v4
	v_mul_lo_u32 v1, v3, v4
	v_mul_hi_u32 v1, v4, v1
	v_add_u32_e32 v1, v4, v1
	v_mul_hi_u32 v1, v5, v1
	v_mul_lo_u32 v3, v1, v2
	v_sub_u32_e32 v3, v5, v3
	v_add_u32_e32 v4, 1, v1
	v_cmp_ge_u32_e32 vcc, v3, v2
	s_nop 1
	v_cndmask_b32_e32 v1, v1, v4, vcc
	v_sub_u32_e32 v4, v3, v2
	v_cndmask_b32_e32 v3, v3, v4, vcc
	v_add_u32_e32 v4, 1, v1
	v_cmp_ge_u32_e32 vcc, v3, v2
	v_add_u32_e32 v3, 1, v5
	s_nop 0
	v_cndmask_b32_e32 v1, v1, v4, vcc
	v_mul_lo_u32 v4, v2, v1
	v_add_u32_e32 v2, v4, v2
	v_cmp_ne_u32_e32 vcc, v3, v2
	s_and_saveexec_b64 s[12:13], vcc
	s_xor_b64 s[12:13], exec, s[12:13]
	s_cbranch_execz .LBB0_1442
	s_waitcnt lgkmcnt(0)
	v_mov_b32_e32 v0, 0x3100
	global_load_dword v0, v0, s[8:9] offset:1024 sc1
	s_add_u32 s18, s8, 0x3500
	s_addc_u32 s19, s9, 0
	s_waitcnt vmcnt(0)
	v_cmp_eq_u32_e32 vcc, v0, v1
	s_and_saveexec_b64 s[16:17], vcc
	s_cbranch_execz .LBB0_1441
	s_mov_b32 s42, 1
	s_mov_b64 s[24:25], 0
	s_branch .LBB0_1432
